# E30-E32: serialized load/wait chains de-serialized (P0 row loads issued together; P0 weight-transpose jobs load both rows before one wait; P1 na_k row-norm gains loaded once up front)
# speedup vs baseline: 1.0471x; 1.0177x over previous
; DEVINL unsigned cvtpk(float lo, float hi) { unsigned r; asm("v_cvt_pk_bf16_f32 %0, %1, %2" : "=v"(r) : "v"(lo), "v"(hi)); return r; }
; DEVINL void phase_prep(const Params& p, char* lds) {
;     ...
;   for (int row = blockIdx.x * 8 + wave; row < LP; row += gridDim.x * 8) {
;     bf16_t* dst = Hb + (size_t)row * DM;
;     if (row < L) {
;       const float* src = row < NMETA ? p.meta + (size_t)row * DM : p.x + (size_t)(row - NMETA) * DM;
;       float ss = 0.f;
; #pragma unroll
;       for (int i = 0; i < 4; ++i) {
;         float4 v = *reinterpret_cast<const float4*>(src + (lane + 64 * i) * 4);
;         ss += v.x * v.x + v.y * v.y + v.z * v.z + v.w * v.w;
;         u32x2 w = {cvtpk(v.x, v.y), cvtpk(v.z, v.w)};
;         *reinterpret_cast<u32x2*>(dst + (lane + 64 * i) * 4) = w;
;       }
; #pragma unroll
;       for (int o = 32; o >= 1; o >>= 1) ss += __shfl_xor(ss, o);
;       if (lane == 0) r1[row] = rsqrtf(ss * (1.f / DM) + EPS);
.LBB0_24:
	v_add_u32_e32 v2, -16, v0
	v_lshlrev_b64 v[20:21], 10, v[0:1]
	v_lshlrev_b64 v[22:23], 12, v[2:3]
	v_lshl_add_u64 v[20:21], v[20:21], 2, s[38:39]
	v_lshl_add_u64 v[22:23], s[36:37], 0, v[22:23]
	v_cmp_gt_i32_e64 s[4:5], 16, v0
	v_mov_b32_e32 v7, v3
	v_mov_b32_e32 v5, v3
	v_cndmask_b32_e64 v21, v23, v21, s[4:5]
	v_cndmask_b32_e64 v20, v22, v20, s[4:5]
	v_lshl_add_u64 v[32:33], v[20:21], 0, v[6:7]
	v_lshl_add_u64 v[8:9], v[8:9], 0, v[4:5]
	global_load_dwordx4 v[20:23], v[32:33], off
	global_load_dwordx4 v[24:27], v[32:33], off offset:1024
	global_load_dwordx4 v[28:31], v[32:33], off offset:2048
	global_load_dwordx4 v[32:35], v[32:33], off offset:3072
	v_cmp_lt_i32_e64 s[4:5], v13, v12
	s_waitcnt vmcnt(0)
	v_cvt_pk_bf16_f32 v36, v20, v21
	v_cvt_pk_bf16_f32 v37, v22, v23
	flat_store_dwordx2 v[8:9], v[36:37]
	v_cvt_pk_bf16_f32 v38, v24, v25
	v_cvt_pk_bf16_f32 v39, v26, v27
	flat_store_dwordx2 v[8:9], v[38:39] offset:512
	v_cvt_pk_bf16_f32 v40, v28, v29
	v_cvt_pk_bf16_f32 v41, v30, v31
	flat_store_dwordx2 v[8:9], v[40:41] offset:1024
	v_mul_f32_e32 v5, v21, v21
	v_fmac_f32_e32 v5, v20, v20
	v_fmac_f32_e32 v5, v22, v22
	v_fmac_f32_e32 v5, v23, v23
	v_mul_f32_e32 v7, v25, v25
	v_fmac_f32_e32 v7, v24, v24
	v_fmac_f32_e32 v7, v26, v26
	v_fmac_f32_e32 v7, v27, v27
	v_add_f32_e32 v5, v5, v7
	v_mul_f32_e32 v7, v29, v29
	v_fmac_f32_e32 v7, v28, v28
	v_fmac_f32_e32 v7, v30, v30
	v_fmac_f32_e32 v7, v31, v31
	v_add_f32_e32 v5, v5, v7
	v_mul_f32_e32 v7, v33, v33
	v_fmac_f32_e32 v7, v32, v32
	v_fmac_f32_e32 v7, v34, v34
	v_cndmask_b32_e64 v2, v11, v13, s[4:5]
	v_fmac_f32_e32 v7, v35, v35
	v_lshlrev_b32_e32 v2, 2, v2
	v_add_f32_e32 v5, v5, v7
	ds_bpermute_b32 v2, v2, v5
	v_cmp_lt_i32_e64 s[4:5], v14, v12
	v_cvt_pk_bf16_f32 v20, v32, v33
	v_cvt_pk_bf16_f32 v21, v34, v35
	flat_store_dwordx2 v[8:9], v[20:21] offset:1536
	s_waitcnt lgkmcnt(0)
	v_add_f32_e32 v2, v5, v2
	v_cndmask_b32_e64 v7, v11, v14, s[4:5]
	v_lshlrev_b32_e32 v7, 2, v7
	ds_bpermute_b32 v5, v7, v2
	v_cmp_lt_i32_e64 s[4:5], v15, v12
	s_waitcnt lgkmcnt(0)
	v_add_f32_e32 v2, v2, v5
	v_cndmask_b32_e64 v7, v11, v15, s[4:5]
	v_lshlrev_b32_e32 v7, 2, v7
	ds_bpermute_b32 v5, v7, v2
	v_cmp_lt_i32_e64 s[4:5], v16, v12
	s_waitcnt lgkmcnt(0)
	v_add_f32_e32 v2, v2, v5
	v_cndmask_b32_e64 v7, v11, v16, s[4:5]
	v_lshlrev_b32_e32 v7, 2, v7
	ds_bpermute_b32 v5, v7, v2
	v_cmp_lt_i32_e64 s[4:5], v17, v12
	s_waitcnt lgkmcnt(0)
	v_add_f32_e32 v2, v2, v5
	v_cndmask_b32_e64 v7, v11, v17, s[4:5]
	v_lshlrev_b32_e32 v7, 2, v7
	ds_bpermute_b32 v5, v7, v2
	v_cmp_lt_i32_e64 s[4:5], v18, v12
	s_waitcnt lgkmcnt(0)
	v_add_f32_e32 v5, v2, v5
	v_cndmask_b32_e64 v7, v11, v18, s[4:5]
	v_lshlrev_b32_e32 v2, 2, v7
	ds_bpermute_b32 v7, v2, v5
	s_mov_b64 s[4:5], s[20:21]
	s_and_saveexec_b64 s[24:25], vcc
	s_cbranch_execz .LBB0_26
	s_waitcnt lgkmcnt(0)
	v_add_f32_e32 v2, v5, v7
	v_fmamk_f32 v2, v2, 0x3a800000, v10
	v_mul_f32_e32 v5, 0x4b800000, v2
	v_cmp_gt_f32_e64 s[4:5], s27, v2
	s_nop 1
	v_cndmask_b32_e64 v2, v2, v5, s[4:5]
	v_rsq_f32_e32 v2, v2
	s_nop 0
	v_mul_f32_e32 v5, 0x45800000, v2
	v_cndmask_b32_e64 v2, v2, v5, s[4:5]
	s_or_b64 s[4:5], s[20:21], exec

; DEVINL void tr_tile(const Params& p, const float* __restrict__ src, int sld, int sc0, int k0, const float* __restrict__ scale, bf16_t* __restrict__ dst, int dld, int n0, float* tile) {
;     ...
;   {
;     const int kk = tid >> 4, nn = (tid & 15) * 4;
; #pragma unroll
;     for (int i = 0; i < 2; ++i) {
;       const int k = kk + i * 32;
;       float4 v = make_float4(0.f, 0.f, 0.f, 0.f);
;       if (sc0 >= 0) {
;         v = *reinterpret_cast<const float4*>(src + (size_t)(k0 + k) * sld + sc0 + nn);
;         const float s = scale ? scale[k0 + k] : 1.f;
;         v.x *= s; v.y *= s; v.z *= s; v.w *= s;
;       }
;       tile[k * 65 + nn + 0] = v.x; tile[k * 65 + nn + 1] = v.y; tile[k * 65 + nn + 2] = v.z; tile[k * 65 + nn + 3] = v.w;
;     }
;   }
.LBB0_42:
	s_lshl_b32 s4, s31, 6
	s_and_b32 s24, s4, 0xc0
	v_mbcnt_lo_u32_b32 v0, -1, 0
	v_mbcnt_hi_u32_b32 v0, -1, v0
	s_cmp_gt_i32 s22, -1
	v_add_u32_e32 v13, s3, v0
	v_lshlrev_b32_e32 v0, 2, v13
	s_cselect_b64 s[26:27], -1, 0
	s_lshl_b64 s[4:5], s[22:23], 2
	v_and_b32_e32 v7, 60, v0
	s_add_u32 s4, s50, s4
	s_addc_u32 s5, s51, s5
	v_lshlrev_b32_e32 v4, 2, v7
	v_ashrrev_i32_e32 v6, 4, v13
	s_cmp_lt_i32 s22, 0
	v_lshl_add_u64 v[8:9], s[4:5], 0, v[4:5]
	v_cmp_ne_u32_e64 s[4:5], 1, v12
	s_barrier
	s_cbranch_scc1 .LBB0_45
	v_add_u32_e32 v10, s24, v6
	v_ashrrev_i32_e32 v11, 31, v10
	v_lshlrev_b64 v[0:1], 13, v[10:11]
	v_lshl_add_u64 v[0:1], v[8:9], 0, v[0:1]
	s_mov_b64 s[98:99], 0x40000
	v_lshl_add_u64 v[42:43], v[0:1], 0, s[98:99]
	global_load_dwordx4 v[0:3], v[0:1], off
	global_load_dwordx4 v[36:39], v[42:43], off
	s_and_b64 vcc, exec, s[4:5]
	s_cbranch_vccnz .LBB0_46
	v_lshl_add_u64 v[10:11], v[10:11], 2, s[46:47]
	global_load_dword v4, v[10:11], off
	global_load_dword v40, v[10:11], off offset:128
	s_branch .LBB0_47

; DEVINL void tr_tile(const Params& p, const float* __restrict__ src, int sld, int sc0, int k0, const float* __restrict__ scale, bf16_t* __restrict__ dst, int dld, int n0, float* tile) {
;     ...
;     for (int i = 0; i < 2; ++i) {
;       const int k = kk + i * 32;
;       float4 v = make_float4(0.f, 0.f, 0.f, 0.f);
;       if (sc0 >= 0) {
;         v = *reinterpret_cast<const float4*>(src + (size_t)(k0 + k) * sld + sc0 + nn);
;         const float s = scale ? scale[k0 + k] : 1.f;
;         v.x *= s; v.y *= s; v.z *= s; v.w *= s;
;       }
;       tile[k * 65 + nn + 0] = v.x; tile[k * 65 + nn + 1] = v.y; tile[k * 65 + nn + 2] = v.z; tile[k * 65 + nn + 3] = v.w;
;     }
.LBB0_48:
	v_lshl_add_u32 v2, v7, 2, 0
	v_mul_lo_u32 v3, v6, s28
	v_add_u32_e32 v14, v2, v3
	s_andn2_b64 vcc, exec, s[26:27]
	ds_write2_b32 v14, v10, v11 offset1:1
	ds_write2_b32 v14, v0, v1 offset0:2 offset1:3
	s_cbranch_vccnz .LBB0_51
	v_add3_u32 v0, v6, s24, 32
	v_ashrrev_i32_e32 v1, 31, v0
	v_lshlrev_b64 v[0:1], 13, v[0:1]
	v_lshl_add_u64 v[0:1], v[8:9], 0, v[0:1]
	v_mov_b64_e32 v[0:1], v[36:37]
	v_mov_b64_e32 v[2:3], v[38:39]
	s_and_b64 vcc, exec, s[4:5]
	s_cbranch_vccnz .LBB0_52
	s_mov_b32 s25, s23
	v_ashrrev_i32_e32 v7, 31, v6
	v_lshl_add_u64 v[6:7], v[6:7], 0, s[24:25]
	v_lshl_add_u64 v[6:7], v[6:7], 2, s[46:47]
	v_mov_b32_e32 v4, v40
	s_branch .LBB0_53

; DEVINL void tr_tile(const Params& p, const float* __restrict__ src, int sld, int sc0, int k0, const float* __restrict__ scale, bf16_t* __restrict__ dst, int dld, int n0, float* tile) {
;     ...
;   {
;     const int kk = tid >> 4, nn = (tid & 15) * 4;
; #pragma unroll
;     for (int i = 0; i < 2; ++i) {
;       const int k = kk + i * 32;
;       float4 v = make_float4(0.f, 0.f, 0.f, 0.f);
;       if (sc0 >= 0) {
;         v = *reinterpret_cast<const float4*>(src + (size_t)(k0 + k) * sld + sc0 + nn);
;         const float s = scale ? scale[k0 + k] : 1.f;
;         v.x *= s; v.y *= s; v.z *= s; v.w *= s;
;       }
;       tile[k * 65 + nn + 0] = v.x; tile[k * 65 + nn + 1] = v.y; tile[k * 65 + nn + 2] = v.z; tile[k * 65 + nn + 3] = v.w;
;     }
;   }
.LBB0_61:
	s_lshl_b32 s4, s31, 6
	s_and_b32 s24, s4, 0xc0
	v_mbcnt_lo_u32_b32 v0, -1, 0
	v_mbcnt_hi_u32_b32 v0, -1, v0
	s_cmp_gt_i32 s22, -1
	v_add_u32_e32 v13, s3, v0
	v_lshlrev_b32_e32 v0, 2, v13
	s_cselect_b64 s[26:27], -1, 0
	s_lshl_b64 s[4:5], s[22:23], 2
	v_and_b32_e32 v7, 60, v0
	s_add_u32 s4, s48, s4
	s_addc_u32 s5, s49, s5
	v_lshlrev_b32_e32 v4, 2, v7
	v_cndmask_b32_e64 v0, 0, 1, s[18:19]
	v_ashrrev_i32_e32 v6, 4, v13
	s_cmp_lt_i32 s22, 0
	v_lshl_add_u64 v[8:9], s[4:5], 0, v[4:5]
	v_cmp_ne_u32_e64 s[4:5], 1, v0
	s_barrier
	s_cbranch_scc1 .LBB0_64
	v_add_u32_e32 v10, s24, v6
	v_mad_i64_i32 v[0:1], s[34:35], v10, s29, v[8:9]
	s_lshl_b32 s98, s29, 5
	s_mov_b32 s99, 0
	v_lshl_add_u64 v[42:43], v[0:1], 0, s[98:99]
	global_load_dwordx4 v[0:3], v[0:1], off
	global_load_dwordx4 v[36:39], v[42:43], off
	s_and_b64 vcc, exec, s[4:5]
	s_cbranch_vccnz .LBB0_65
	v_ashrrev_i32_e32 v11, 31, v10
	v_lshl_add_u64 v[10:11], v[10:11], 2, s[44:45]
	global_load_dword v4, v[10:11], off
	global_load_dword v40, v[10:11], off offset:128
	s_branch .LBB0_66

; DEVINL void tr_tile(const Params& p, const float* __restrict__ src, int sld, int sc0, int k0, const float* __restrict__ scale, bf16_t* __restrict__ dst, int dld, int n0, float* tile) {
;     ...
;     for (int i = 0; i < 2; ++i) {
;       const int k = kk + i * 32;
;       float4 v = make_float4(0.f, 0.f, 0.f, 0.f);
;       if (sc0 >= 0) {
;         v = *reinterpret_cast<const float4*>(src + (size_t)(k0 + k) * sld + sc0 + nn);
;         const float s = scale ? scale[k0 + k] : 1.f;
;         v.x *= s; v.y *= s; v.z *= s; v.w *= s;
;       }
;       tile[k * 65 + nn + 0] = v.x; tile[k * 65 + nn + 1] = v.y; tile[k * 65 + nn + 2] = v.z; tile[k * 65 + nn + 3] = v.w;
;     }
.LBB0_67:
	v_lshl_add_u32 v2, v7, 2, 0
	v_mul_lo_u32 v3, v6, s28
	v_add_u32_e32 v14, v2, v3
	s_andn2_b64 vcc, exec, s[26:27]
	ds_write2_b32 v14, v10, v11 offset1:1
	ds_write2_b32 v14, v0, v1 offset0:2 offset1:3
	s_cbranch_vccnz .LBB0_70
	v_add3_u32 v0, v6, s24, 32
	v_mad_i64_i32 v[0:1], s[26:27], v0, s29, v[8:9]
	v_mov_b64_e32 v[0:1], v[36:37]
	v_mov_b64_e32 v[2:3], v[38:39]
	s_and_b64 vcc, exec, s[4:5]
	s_cbranch_vccnz .LBB0_71
	s_mov_b32 s25, s23
	v_ashrrev_i32_e32 v7, 31, v6
	v_lshl_add_u64 v[6:7], v[6:7], 0, s[24:25]
	v_lshl_add_u64 v[6:7], v[6:7], 2, s[44:45]
	v_mov_b32_e32 v4, v40
	s_branch .LBB0_72

; DEVINL void tr_tile(const Params& p, const float* __restrict__ src, int sld, int sc0, int k0, const float* __restrict__ scale, bf16_t* __restrict__ dst, int dld, int n0, float* tile) {
;     ...
;   {
;     const int kk = tid >> 4, nn = (tid & 15) * 4;
; #pragma unroll
;     for (int i = 0; i < 2; ++i) {
;       const int k = kk + i * 32;
;       float4 v = make_float4(0.f, 0.f, 0.f, 0.f);
;       if (sc0 >= 0) {
;         v = *reinterpret_cast<const float4*>(src + (size_t)(k0 + k) * sld + sc0 + nn);
;         const float s = scale ? scale[k0 + k] : 1.f;
;         v.x *= s; v.y *= s; v.z *= s; v.w *= s;
;       }
;       tile[k * 65 + nn + 0] = v.x; tile[k * 65 + nn + 1] = v.y; tile[k * 65 + nn + 2] = v.z; tile[k * 65 + nn + 3] = v.w;
;     }
;   }
.LBB0_97:
	s_lshl_b32 s4, s31, 6
	s_and_b32 s24, s4, 0x3c0
	v_mbcnt_lo_u32_b32 v0, -1, 0
	v_mbcnt_hi_u32_b32 v0, -1, v0
	s_cmp_gt_i32 s22, -1
	v_add_u32_e32 v13, s3, v0
	v_lshlrev_b32_e32 v0, 2, v13
	s_cselect_b64 s[26:27], -1, 0
	s_lshl_b64 s[4:5], s[22:23], 2
	v_and_b32_e32 v7, 60, v0
	s_add_u32 s4, s42, s4
	s_addc_u32 s5, s43, s5
	v_lshlrev_b32_e32 v4, 2, v7
	v_cndmask_b32_e64 v0, 0, 1, s[20:21]
	v_ashrrev_i32_e32 v6, 4, v13
	s_cmp_lt_i32 s22, 0
	v_lshl_add_u64 v[8:9], s[4:5], 0, v[4:5]
	v_cmp_ne_u32_e64 s[4:5], 1, v0
	s_barrier
	s_cbranch_scc1 .LBB0_100
	v_add_u32_e32 v10, s24, v6
	v_mad_i64_i32 v[0:1], s[34:35], v10, s30, v[8:9]
	s_lshl_b32 s98, s30, 5
	s_mov_b32 s99, 0
	v_lshl_add_u64 v[42:43], v[0:1], 0, s[98:99]
	global_load_dwordx4 v[0:3], v[0:1], off
	global_load_dwordx4 v[36:39], v[42:43], off
	s_and_b64 vcc, exec, s[4:5]
	s_cbranch_vccnz .LBB0_101
	v_ashrrev_i32_e32 v11, 31, v10
	v_lshl_add_u64 v[10:11], v[10:11], 2, s[40:41]
	global_load_dword v4, v[10:11], off
	global_load_dword v40, v[10:11], off offset:128
	s_branch .LBB0_102

; DEVINL void tr_tile(const Params& p, const float* __restrict__ src, int sld, int sc0, int k0, const float* __restrict__ scale, bf16_t* __restrict__ dst, int dld, int n0, float* tile) {
;     ...
;     for (int i = 0; i < 2; ++i) {
;       const int k = kk + i * 32;
;       float4 v = make_float4(0.f, 0.f, 0.f, 0.f);
;       if (sc0 >= 0) {
;         v = *reinterpret_cast<const float4*>(src + (size_t)(k0 + k) * sld + sc0 + nn);
;         const float s = scale ? scale[k0 + k] : 1.f;
;         v.x *= s; v.y *= s; v.z *= s; v.w *= s;
;       }
;       tile[k * 65 + nn + 0] = v.x; tile[k * 65 + nn + 1] = v.y; tile[k * 65 + nn + 2] = v.z; tile[k * 65 + nn + 3] = v.w;
;     }
.LBB0_103:
	v_lshl_add_u32 v2, v7, 2, 0
	v_mul_lo_u32 v3, v6, s28
	v_add_u32_e32 v14, v2, v3
	s_andn2_b64 vcc, exec, s[26:27]
	ds_write2_b32 v14, v10, v11 offset1:1
	ds_write2_b32 v14, v0, v1 offset0:2 offset1:3
	s_cbranch_vccnz .LBB0_30
	v_add3_u32 v0, v6, s24, 32
	v_mad_i64_i32 v[0:1], s[26:27], v0, s30, v[8:9]
	v_mov_b64_e32 v[0:1], v[36:37]
	v_mov_b64_e32 v[2:3], v[38:39]
	s_and_b64 vcc, exec, s[4:5]
	s_cbranch_vccnz .LBB0_106
	s_mov_b32 s25, s23
	v_ashrrev_i32_e32 v7, 31, v6
	v_lshl_add_u64 v[6:7], v[6:7], 0, s[24:25]
	v_lshl_add_u64 v[6:7], v[6:7], 2, s[40:41]
	v_mov_b32_e32 v4, v40
	s_branch .LBB0_107

; DEVINL int tidx(const Params& p) { int l; asm volatile("v_mbcnt_lo_u32_b32 %0, -1, 0\n\tv_mbcnt_hi_u32_b32 %0, -1, %0" : "=v"(l)); return p.tid0 + l; }
; DEVINL unsigned char* wsp(const Params& p) { unsigned char* w = p.ws; asm volatile("" : "+s"(w)); return w; }
; DEVINL float bflo(unsigned u) { return __uint_as_float(u << 16); }
; DEVINL float bfhi(unsigned u) { return __uint_as_float(u & 0xffff0000u); }
; DEVINL void nak_group(const Params& p, int t, int h) {
;   bf16_t* NAK = (bf16_t*)(wsp(p) + OFF_NAK);
;   const int blk = t < NMETA ? 0 : 1 + ((t - NMETA) >> 5), r32 = t < NMETA ? t : ((t - NMETA) & 31);
;   bf16_t* base = NAK + (size_t)(h * 513 + blk) * 2048 + r32 * 8;
;   u32x4 raw[8];
; #pragma unroll
;   for (int pc = 0; pc < 8; ++pc) raw[pc] = *reinterpret_cast<const u32x4*>(base + pc * 256);
;   float ss = 0.f;
; #pragma unroll
;   for (int pc = 0; pc < 8; ++pc)
; #pragma unroll
;     for (int j = 0; j < 4; ++j) { const float a = bflo(raw[pc][j]), b = bfhi(raw[pc][j]); ss += a * a + b * b; }
;   const float r = rsqrtf(ss * (1.f / 64.f) + EPS);
; DEVINL void phase_gemm1(const Params& p, char* lds) {
;     ...
;       asm volatile("s_waitcnt vmcnt(0)" ::: "memory"); __syncthreads();
;       { const int tid = tidx(p), t = brow + (tid & 255);
;         if (t < L) { const int h0 = (pn - 10) * 4 + (tid >> 8) * 2; nak_group(p, t, h0); nak_group(p, t, h0 + 1); } }
.LBB0_348:
	s_or_b64 exec, exec, s[4:5]
	global_load_dwordx4 v[172:175], v129, s[62:63]
	global_load_dwordx4 v[176:179], v129, s[62:63] offset:16
	global_load_dwordx4 v[180:183], v129, s[62:63] offset:32
	global_load_dwordx4 v[184:187], v129, s[62:63] offset:48
	global_load_dwordx4 v[188:191], v129, s[62:63] offset:64
	global_load_dwordx4 v[192:195], v129, s[62:63] offset:80
	global_load_dwordx4 v[196:199], v129, s[62:63] offset:96
	global_load_dwordx4 v[200:203], v129, s[62:63] offset:112
	global_load_dwordx4 v[204:207], v129, s[62:63] offset:128
	global_load_dwordx4 v[208:211], v129, s[62:63] offset:144
	global_load_dwordx4 v[212:215], v129, s[62:63] offset:160
	global_load_dwordx4 v[216:219], v129, s[62:63] offset:176
	global_load_dwordx4 v[220:223], v129, s[62:63] offset:192
	global_load_dwordx4 v[224:227], v129, s[62:63] offset:208
	global_load_dwordx4 v[228:231], v129, s[62:63] offset:224
	global_load_dwordx4 v[232:235], v129, s[62:63] offset:240
	s_waitcnt vmcnt(0)
	s_waitcnt vmcnt(0) lgkmcnt(0)
	s_barrier
	v_mbcnt_lo_u32_b32 v0, -1, 0
	v_mbcnt_hi_u32_b32 v0, -1, v0
	s_nop 0
	v_add_u32_e32 v1, s3, v0
	v_or_b32_sdwa v0, v1, s80 dst_sel:DWORD dst_unused:UNUSED_PAD src0_sel:BYTE_0 src1_sel:DWORD
	v_cmp_gt_i32_e32 vcc, s33, v0
	s_and_saveexec_b64 s[4:5], vcc
	s_cbranch_execz .LBB0_350
	v_add_u32_e32 v3, -16, v0
	s_lshl_b32 s6, s78, 2
	v_ashrrev_i32_e32 v1, 7, v1
	v_lshrrev_b32_e32 v2, 5, v3
	s_sub_i32 s6, s6, 40
	v_and_b32_e32 v1, -2, v1
	v_cmp_gt_i32_e32 vcc, 16, v0
	v_add_u32_e32 v2, 1, v2
	v_and_b32_e32 v3, 31, v3
	v_add_u32_e32 v1, s6, v1
	v_cndmask_b32_e64 v2, v2, 0, vcc
	v_cndmask_b32_e32 v3, v3, v0, vcc
	s_movk_i32 s8, 0x201
	v_mad_u64_u32 v[22:23], s[8:9], v1, s8, v[2:3]
	v_ashrrev_i32_e32 v23, 31, v22
	v_lshlrev_b32_e32 v2, 3, v3
	s_mov_b64 s[6:7], s[72:73]
	v_lshlrev_b64 v[0:1], 12, v[22:23]
	v_ashrrev_i32_e32 v3, 31, v2
	v_lshlrev_b64 v[20:21], 1, v[2:3]
	v_lshl_add_u64 v[0:1], s[6:7], 0, v[0:1]
	v_lshl_add_u64 v[0:1], v[0:1], 0, v[20:21]
	s_mov_b32 s10, 0x2858000
	v_add_co_u32_e32 v32, vcc, s10, v0
	s_mov_b64 s[8:9], 0x2858400
	s_nop 0
	v_addc_co_u32_e32 v33, vcc, 0, v1, vcc
	v_lshl_add_u64 v[24:25], v[0:1], 0, s[8:9]
	flat_load_dwordx4 v[26:29], v[32:33] offset:1024
	flat_load_dwordx4 v[34:37], v[24:25] offset:512
	flat_load_dwordx4 v[38:41], v[24:25] offset:1024
	flat_load_dwordx4 v[16:19], v[24:25] offset:1536
	flat_load_dwordx4 v[12:15], v[24:25] offset:2048
	flat_load_dwordx4 v[8:11], v[24:25] offset:2560
	flat_load_dwordx4 v[4:7], v[24:25] offset:3072
	flat_load_dwordx4 v[0:3], v[24:25] offset:3584
	s_mov_b32 s11, 0x800000
	s_mov_b64 s[6:7], s[72:73]
	s_waitcnt vmcnt(0) lgkmcnt(0)
	v_and_b32_e32 v73, 0xffff0000, v26
	v_and_b32_e32 v74, 0xffff0000, v27
	v_lshlrev_b32_e32 v77, 16, v26
	v_mul_f32_e32 v23, v73, v73
	v_lshlrev_b32_e32 v75, 16, v27
	v_mul_f32_e32 v26, v74, v74
	v_fmac_f32_e32 v23, v77, v77
	v_fmac_f32_e32 v26, v75, v75
	v_and_b32_e32 v60, 0xffff0000, v28
	v_add_f32_e32 v23, v23, v26
	v_lshlrev_b32_e32 v76, 16, v28
	v_mul_f32_e32 v26, v60, v60
	v_fmac_f32_e32 v26, v76, v76
	v_and_b32_e32 v63, 0xffff0000, v29
	v_add_f32_e32 v23, v26, v23
	v_lshlrev_b32_e32 v64, 16, v29
	v_mul_f32_e32 v26, v63, v63
	v_fmac_f32_e32 v26, v64, v64
	v_and_b32_e32 v68, 0xffff0000, v34
	v_add_f32_e32 v23, v26, v23
	v_lshlrev_b32_e32 v69, 16, v34
	v_mul_f32_e32 v26, v68, v68
	v_fmac_f32_e32 v26, v69, v69
	v_and_b32_e32 v70, 0xffff0000, v35
	v_add_f32_e32 v23, v26, v23
	v_lshlrev_b32_e32 v71, 16, v35
	v_mul_f32_e32 v26, v70, v70
	v_fmac_f32_e32 v26, v71, v71
	v_and_b32_e32 v49, 0xffff0000, v36
	v_add_f32_e32 v23, v26, v23
	v_lshlrev_b32_e32 v72, 16, v36
	v_mul_f32_e32 v26, v49, v49
	v_fmac_f32_e32 v26, v72, v72
	v_and_b32_e32 v56, 0xffff0000, v37
	v_add_f32_e32 v23, v26, v23
	v_lshlrev_b32_e32 v57, 16, v37
	v_mul_f32_e32 v26, v56, v56
	v_fmac_f32_e32 v26, v57, v57
	v_and_b32_e32 v58, 0xffff0000, v38
	v_add_f32_e32 v23, v26, v23
	v_lshlrev_b32_e32 v59, 16, v38
	v_mul_f32_e32 v26, v58, v58
	v_fmac_f32_e32 v26, v59, v59
	v_and_b32_e32 v61, 0xffff0000, v39
	v_add_f32_e32 v23, v26, v23
	v_lshlrev_b32_e32 v62, 16, v39
	v_mul_f32_e32 v26, v61, v61
	v_fmac_f32_e32 v26, v62, v62
	v_and_b32_e32 v45, 0xffff0000, v40
	v_add_f32_e32 v23, v26, v23
	v_lshlrev_b32_e32 v65, 16, v40
	v_mul_f32_e32 v26, v45, v45
	v_fmac_f32_e32 v26, v65, v65
	v_and_b32_e32 v46, 0xffff0000, v41
	v_add_f32_e32 v23, v26, v23
	v_lshlrev_b32_e32 v47, 16, v41
	v_mul_f32_e32 v26, v46, v46
	v_and_b32_e32 v41, 0xffff0000, v16
	v_fmac_f32_e32 v26, v47, v47
	v_lshlrev_b32_e32 v42, 16, v16
	v_mul_f32_e32 v16, v41, v41
	v_and_b32_e32 v43, 0xffff0000, v17
	v_add_f32_e32 v23, v26, v23
	v_fmac_f32_e32 v16, v42, v42
	v_lshlrev_b32_e32 v44, 16, v17
	v_mul_f32_e32 v17, v43, v43
	v_add_f32_e32 v16, v16, v23
	v_fmac_f32_e32 v17, v44, v44
	v_and_b32_e32 v55, 0xffff0000, v18
	v_add_f32_e32 v16, v17, v16
	v_lshlrev_b32_e32 v48, 16, v18
	v_mul_f32_e32 v17, v55, v55
	v_fmac_f32_e32 v17, v48, v48
	v_and_b32_e32 v66, 0xffff0000, v19
	v_add_f32_e32 v16, v17, v16
	v_lshlrev_b32_e32 v67, 16, v19
	v_mul_f32_e32 v17, v66, v66
	v_and_b32_e32 v50, 0xffff0000, v12
	v_fmac_f32_e32 v17, v67, v67
	v_lshlrev_b32_e32 v54, 16, v12
	v_mul_f32_e32 v12, v50, v50
	v_and_b32_e32 v51, 0xffff0000, v13
	v_add_f32_e32 v16, v17, v16
	v_fmac_f32_e32 v12, v54, v54
	v_lshlrev_b32_e32 v52, 16, v13
	v_mul_f32_e32 v13, v51, v51
	v_add_f32_e32 v12, v12, v16
	v_fmac_f32_e32 v13, v52, v52
	v_and_b32_e32 v40, 0xffff0000, v14
	v_add_f32_e32 v12, v13, v12
	v_lshlrev_b32_e32 v53, 16, v14
	v_mul_f32_e32 v13, v40, v40
	v_fmac_f32_e32 v13, v53, v53
	v_and_b32_e32 v38, 0xffff0000, v15
	v_add_f32_e32 v12, v13, v12
	v_lshlrev_b32_e32 v39, 16, v15
; DEVINL unsigned cvtpk(float lo, float hi) { unsigned r; asm("v_cvt_pk_bf16_f32 %0, %1, %2" : "=v"(r) : "v"(lo), "v"(hi)); return r; }
; DEVINL float bflo(unsigned u) { return __uint_as_float(u << 16); }
; DEVINL float bfhi(unsigned u) { return __uint_as_float(u & 0xffff0000u); }
; DEVINL void nak_group(const Params& p, int t, int h) {
;     ...
;   for (int pc = 0; pc < 8; ++pc)
; #pragma unroll
;     for (int j = 0; j < 4; ++j) { const float a = bflo(raw[pc][j]), b = bfhi(raw[pc][j]); ss += a * a + b * b; }
;   const float r = rsqrtf(ss * (1.f / 64.f) + EPS);
; #pragma unroll
;   for (int pc = 0; pc < 8; ++pc) {
;     u32x4 o;
; #pragma unroll
;     for (int j = 0; j < 4; ++j) { const int d = pc * 8 + j * 2; o[j] = cvtpk(bflo(raw[pc][j]) * r * p.nak_w[d], bfhi(raw[pc][j]) * r * p.nak_w[d + 1]); }
;     *reinterpret_cast<u32x4*>(base + pc * 256) = o;
	v_mul_f32_e32 v13, v38, v38
	v_and_b32_e32 v34, 0xffff0000, v8
	v_fmac_f32_e32 v13, v39, v39
	v_lshlrev_b32_e32 v37, 16, v8
	v_mul_f32_e32 v8, v34, v34
	v_and_b32_e32 v35, 0xffff0000, v9
	v_add_f32_e32 v12, v13, v12
	v_fmac_f32_e32 v8, v37, v37
	v_lshlrev_b32_e32 v36, 16, v9
	v_mul_f32_e32 v9, v35, v35
	v_add_f32_e32 v8, v8, v12
	v_fmac_f32_e32 v9, v36, v36
	v_and_b32_e32 v29, 0xffff0000, v11
	v_and_b32_e32 v28, 0xffff0000, v10
	v_add_f32_e32 v12, v9, v8
	v_lshlrev_b32_e32 v31, 16, v11
	v_lshlrev_b32_e32 v30, 16, v10
	v_pk_mul_f32 v[8:9], v[28:29], v[28:29]
	v_and_b32_e32 v19, 0xffff0000, v5
	v_pk_fma_f32 v[8:9], v[30:31], v[30:31], v[8:9]
	v_and_b32_e32 v18, 0xffff0000, v4
	v_add_f32_e32 v8, v8, v12
	v_lshlrev_b32_e32 v27, 16, v5
	v_lshlrev_b32_e32 v26, 16, v4
	v_pk_mul_f32 v[4:5], v[18:19], v[18:19]
	v_add_f32_e32 v8, v9, v8
	v_pk_fma_f32 v[4:5], v[26:27], v[26:27], v[4:5]
	v_and_b32_e32 v15, 0xffff0000, v7
	v_add_f32_e32 v4, v4, v8
	v_and_b32_e32 v14, 0xffff0000, v6
	v_add_f32_e32 v8, v5, v4
	v_lshlrev_b32_e32 v17, 16, v7
	v_lshlrev_b32_e32 v16, 16, v6
	v_pk_mul_f32 v[4:5], v[14:15], v[14:15]
	v_and_b32_e32 v11, 0xffff0000, v1
	v_pk_fma_f32 v[4:5], v[16:17], v[16:17], v[4:5]
	v_and_b32_e32 v10, 0xffff0000, v0
	v_add_f32_e32 v4, v4, v8
	v_lshlrev_b32_e32 v13, 16, v1
	v_lshlrev_b32_e32 v12, 16, v0
	v_pk_mul_f32 v[0:1], v[10:11], v[10:11]
	v_add_f32_e32 v4, v5, v4
	v_pk_fma_f32 v[0:1], v[12:13], v[12:13], v[0:1]
	v_and_b32_e32 v7, 0xffff0000, v3
	v_add_f32_e32 v0, v0, v4
	v_and_b32_e32 v6, 0xffff0000, v2
	v_add_f32_e32 v4, v1, v0
	v_lshlrev_b32_e32 v9, 16, v3
	v_lshlrev_b32_e32 v8, 16, v2
	v_pk_mul_f32 v[0:1], v[6:7], v[6:7]
	s_nop 0
	v_pk_fma_f32 v[0:1], v[8:9], v[8:9], v[0:1]
	s_nop 0
	v_add_f32_e32 v0, v0, v4
	v_add_f32_e32 v0, v1, v0
	v_fmamk_f32 v0, v0, 0x3c800000, v154
	v_cmp_gt_f32_e32 vcc, s11, v0
	v_mul_f32_e32 v1, 0x4b800000, v0
	s_nop 0
	v_cndmask_b32_e32 v0, v0, v1, vcc
	v_rsq_f32_e32 v0, v0
	s_nop 0
	v_mul_f32_e32 v1, 0x45800000, v0
	v_cndmask_b32_e32 v23, v0, v1, vcc
	s_nop 1
	v_mov_b64_e32 v[0:1], v[172:173]
	v_mov_b64_e32 v[2:3], v[174:175]
	v_mul_f32_e32 v4, v23, v77
	v_mul_f32_e32 v60, v23, v60
	v_mul_f32_e32 v30, v23, v30
	v_mul_f32_e32 v28, v23, v28
	v_mul_f32_e32 v16, v23, v16
	v_mul_f32_e32 v14, v23, v14
	v_mul_f32_e32 v8, v23, v8
	v_mul_f32_e32 v6, v23, v6
	s_waitcnt vmcnt(0)
	v_mul_f32_e32 v0, v0, v4
	v_mul_f32_e32 v4, v23, v73
	v_mul_f32_e32 v1, v1, v4
	v_cvt_pk_bf16_f32 v0, v0, v1
	v_mul_f32_e32 v1, v23, v75
	v_mul_f32_e32 v1, v2, v1
	v_mul_f32_e32 v2, v23, v74
	v_mul_f32_e32 v2, v3, v2
	v_cvt_pk_bf16_f32 v1, v1, v2
	s_nop 1
	v_mov_b64_e32 v[2:3], v[176:177]
	v_mov_b64_e32 v[4:5], v[178:179]
	v_mul_f32_e32 v73, v23, v76
	s_waitcnt vmcnt(0)
	v_mul_f32_e32 v2, v2, v73
	v_mul_f32_e32 v3, v3, v60
	v_cvt_pk_bf16_f32 v2, v2, v3
	v_mul_f32_e32 v3, v23, v64
	v_mul_f32_e32 v3, v4, v3
	v_mul_f32_e32 v4, v23, v63
	v_mul_f32_e32 v4, v5, v4
	v_cvt_pk_bf16_f32 v3, v3, v4
	flat_store_dwordx4 v[32:33], v[0:3] offset:1024
	s_nop 1
	v_mov_b64_e32 v[0:1], v[180:181]
	v_mov_b64_e32 v[2:3], v[182:183]
	v_mul_f32_e32 v4, v23, v69
	v_mul_f32_e32 v32, v23, v72
	s_waitcnt vmcnt(0)
	v_mul_f32_e32 v0, v0, v4
	v_mul_f32_e32 v4, v23, v68
	v_mul_f32_e32 v1, v1, v4
	v_cvt_pk_bf16_f32 v0, v0, v1
	v_mul_f32_e32 v1, v23, v71
	v_mul_f32_e32 v1, v2, v1
	v_mul_f32_e32 v2, v23, v70
	v_mul_f32_e32 v2, v3, v2
	v_cvt_pk_bf16_f32 v1, v1, v2
	s_nop 1
	v_mov_b64_e32 v[2:3], v[184:185]
	v_mov_b64_e32 v[4:5], v[186:187]
	s_waitcnt vmcnt(0)
	v_mul_f32_e32 v2, v2, v32
	v_mul_f32_e32 v32, v23, v49
	v_mul_f32_e32 v3, v3, v32
	v_cvt_pk_bf16_f32 v2, v2, v3
	v_mul_f32_e32 v3, v23, v57
	v_mul_f32_e32 v3, v4, v3
	v_mul_f32_e32 v4, v23, v56
	v_mul_f32_e32 v4, v5, v4
	v_cvt_pk_bf16_f32 v3, v3, v4
	flat_store_dwordx4 v[24:25], v[0:3] offset:512
	s_nop 1
	v_mov_b64_e32 v[0:1], v[188:189]
	v_mov_b64_e32 v[2:3], v[190:191]
	v_mul_f32_e32 v4, v23, v59
	v_mul_f32_e32 v32, v23, v65
	s_waitcnt vmcnt(0)
	v_mul_f32_e32 v0, v0, v4
	v_mul_f32_e32 v4, v23, v58
	v_mul_f32_e32 v1, v1, v4
	v_cvt_pk_bf16_f32 v0, v0, v1
	v_mul_f32_e32 v1, v23, v62
	v_mul_f32_e32 v1, v2, v1
	v_mul_f32_e32 v2, v23, v61
	v_mul_f32_e32 v2, v3, v2
	v_cvt_pk_bf16_f32 v1, v1, v2
	s_nop 1
	v_mov_b64_e32 v[2:3], v[192:193]
	v_mov_b64_e32 v[4:5], v[194:195]
	s_waitcnt vmcnt(0)
	v_mul_f32_e32 v2, v2, v32
	v_mul_f32_e32 v32, v23, v45
	v_mul_f32_e32 v3, v3, v32
	v_cvt_pk_bf16_f32 v2, v2, v3
	v_mul_f32_e32 v3, v23, v47
	v_mul_f32_e32 v3, v4, v3
	v_mul_f32_e32 v4, v23, v46
	v_mul_f32_e32 v4, v4, v5
	v_cvt_pk_bf16_f32 v3, v3, v4
	flat_store_dwordx4 v[24:25], v[0:3] offset:1024
	s_nop 1
	v_mov_b64_e32 v[0:1], v[196:197]
	v_mov_b64_e32 v[2:3], v[198:199]
	v_mul_f32_e32 v4, v23, v42
	v_mul_f32_e32 v32, v23, v48
	s_waitcnt vmcnt(0)
	v_mul_f32_e32 v0, v4, v0
	v_mul_f32_e32 v4, v23, v41
	v_mul_f32_e32 v1, v4, v1
	v_cvt_pk_bf16_f32 v0, v0, v1
	v_mul_f32_e32 v1, v23, v44
	v_mul_f32_e32 v1, v1, v2
	v_mul_f32_e32 v2, v23, v43
	v_mul_f32_e32 v2, v2, v3
	v_cvt_pk_bf16_f32 v1, v1, v2
	s_nop 1
	v_mov_b64_e32 v[2:3], v[200:201]
	v_mov_b64_e32 v[4:5], v[202:203]
	s_waitcnt vmcnt(0)
	v_mul_f32_e32 v2, v32, v2
	v_mul_f32_e32 v32, v23, v55
	v_mul_f32_e32 v3, v32, v3
	v_cvt_pk_bf16_f32 v2, v2, v3
	v_mul_f32_e32 v3, v23, v67
	v_mul_f32_e32 v3, v3, v4
	v_mul_f32_e32 v4, v23, v66
	v_mul_f32_e32 v4, v4, v5
	v_cvt_pk_bf16_f32 v3, v3, v4
	flat_store_dwordx4 v[24:25], v[0:3] offset:1536
	s_nop 1
	v_mov_b64_e32 v[0:1], v[204:205]
	v_mov_b64_e32 v[2:3], v[206:207]
	v_mul_f32_e32 v4, v23, v54
	v_mul_f32_e32 v32, v23, v53
	s_waitcnt vmcnt(0)
; DEVINL unsigned char* wsp(const Params& p) { unsigned char* w = p.ws; asm volatile("" : "+s"(w)); return w; }
; DEVINL unsigned cvtpk(float lo, float hi) { unsigned r; asm("v_cvt_pk_bf16_f32 %0, %1, %2" : "=v"(r) : "v"(lo), "v"(hi)); return r; }
; DEVINL float bflo(unsigned u) { return __uint_as_float(u << 16); }
; DEVINL float bfhi(unsigned u) { return __uint_as_float(u & 0xffff0000u); }
; DEVINL void nak_group(const Params& p, int t, int h) {
;   bf16_t* NAK = (bf16_t*)(wsp(p) + OFF_NAK);
;   const int blk = t < NMETA ? 0 : 1 + ((t - NMETA) >> 5), r32 = t < NMETA ? t : ((t - NMETA) & 31);
;   bf16_t* base = NAK + (size_t)(h * 513 + blk) * 2048 + r32 * 8;
;   u32x4 raw[8];
; #pragma unroll
;   for (int pc = 0; pc < 8; ++pc) raw[pc] = *reinterpret_cast<const u32x4*>(base + pc * 256);
;   float ss = 0.f;
; #pragma unroll
;   for (int pc = 0; pc < 8; ++pc)
; #pragma unroll
;     for (int j = 0; j < 4; ++j) { const float a = bflo(raw[pc][j]), b = bfhi(raw[pc][j]); ss += a * a + b * b; }
;     ...
;   for (int pc = 0; pc < 8; ++pc) {
;     u32x4 o;
; #pragma unroll
;     for (int j = 0; j < 4; ++j) { const int d = pc * 8 + j * 2; o[j] = cvtpk(bflo(raw[pc][j]) * r * p.nak_w[d], bfhi(raw[pc][j]) * r * p.nak_w[d + 1]); }
;     *reinterpret_cast<u32x4*>(base + pc * 256) = o;
	v_mul_f32_e32 v0, v4, v0
	v_mul_f32_e32 v4, v23, v50
	v_mul_f32_e32 v1, v4, v1
	v_cvt_pk_bf16_f32 v0, v0, v1
	v_mul_f32_e32 v1, v23, v52
	v_mul_f32_e32 v1, v1, v2
	v_mul_f32_e32 v2, v23, v51
	v_mul_f32_e32 v2, v2, v3
	v_cvt_pk_bf16_f32 v1, v1, v2
	s_nop 1
	v_mov_b64_e32 v[2:3], v[208:209]
	v_mov_b64_e32 v[4:5], v[210:211]
	s_waitcnt vmcnt(0)
	v_mul_f32_e32 v2, v32, v2
	v_mul_f32_e32 v32, v23, v40
	v_mul_f32_e32 v3, v32, v3
	v_cvt_pk_bf16_f32 v2, v2, v3
	v_mul_f32_e32 v3, v23, v39
	v_mul_f32_e32 v3, v3, v4
	v_mul_f32_e32 v4, v23, v38
	v_mul_f32_e32 v4, v4, v5
	v_cvt_pk_bf16_f32 v3, v3, v4
	flat_store_dwordx4 v[24:25], v[0:3] offset:2048
	s_nop 1
	v_mov_b64_e32 v[0:1], v[212:213]
	v_mov_b64_e32 v[2:3], v[214:215]
	v_mul_f32_e32 v4, v23, v37
	s_waitcnt vmcnt(0)
	v_mul_f32_e32 v0, v4, v0
	v_mul_f32_e32 v4, v23, v34
	v_mul_f32_e32 v1, v4, v1
	v_cvt_pk_bf16_f32 v0, v0, v1
	v_mul_f32_e32 v1, v23, v36
	v_mul_f32_e32 v1, v1, v2
	v_mul_f32_e32 v2, v23, v35
	v_mul_f32_e32 v2, v2, v3
	v_cvt_pk_bf16_f32 v1, v1, v2
	s_nop 1
	v_mov_b64_e32 v[2:3], v[216:217]
	v_mov_b64_e32 v[4:5], v[218:219]
	s_waitcnt vmcnt(0)
	v_mul_f32_e32 v2, v30, v2
	v_mul_f32_e32 v3, v28, v3
	v_cvt_pk_bf16_f32 v2, v2, v3
	v_mul_f32_e32 v3, v23, v31
	v_mul_f32_e32 v3, v3, v4
	v_mul_f32_e32 v4, v23, v29
	v_mul_f32_e32 v4, v4, v5
	v_cvt_pk_bf16_f32 v3, v3, v4
	flat_store_dwordx4 v[24:25], v[0:3] offset:2560
	s_nop 1
	v_mov_b64_e32 v[0:1], v[220:221]
	v_mov_b64_e32 v[2:3], v[222:223]
	v_mul_f32_e32 v4, v23, v26
	s_waitcnt vmcnt(0)
	v_mul_f32_e32 v0, v4, v0
	v_mul_f32_e32 v4, v23, v18
	v_mul_f32_e32 v1, v4, v1
	v_cvt_pk_bf16_f32 v0, v0, v1
	v_mul_f32_e32 v1, v23, v27
	v_mul_f32_e32 v1, v1, v2
	v_mul_f32_e32 v2, v23, v19
	v_mul_f32_e32 v2, v2, v3
	v_cvt_pk_bf16_f32 v1, v1, v2
	s_nop 1
	v_mov_b64_e32 v[2:3], v[224:225]
	v_mov_b64_e32 v[4:5], v[226:227]
	s_waitcnt vmcnt(0)
	v_mul_f32_e32 v2, v16, v2
	v_mul_f32_e32 v3, v14, v3
	v_cvt_pk_bf16_f32 v2, v2, v3
	v_mul_f32_e32 v3, v23, v17
	v_mul_f32_e32 v3, v3, v4
	v_mul_f32_e32 v4, v23, v15
	v_mul_f32_e32 v4, v4, v5
	v_cvt_pk_bf16_f32 v3, v3, v4
	flat_store_dwordx4 v[24:25], v[0:3] offset:3072
	s_nop 1
	v_mov_b64_e32 v[0:1], v[228:229]
	v_mov_b64_e32 v[2:3], v[230:231]
	v_mul_f32_e32 v4, v23, v12
	s_waitcnt vmcnt(0)
	v_mul_f32_e32 v0, v4, v0
	v_mul_f32_e32 v4, v23, v10
	v_mul_f32_e32 v1, v4, v1
	v_cvt_pk_bf16_f32 v0, v0, v1
	v_mul_f32_e32 v1, v23, v13
	v_mul_f32_e32 v1, v1, v2
	v_mul_f32_e32 v2, v23, v11
	v_mul_f32_e32 v2, v2, v3
	v_cvt_pk_bf16_f32 v1, v1, v2
	s_nop 1
	v_mov_b64_e32 v[2:3], v[232:233]
	v_mov_b64_e32 v[4:5], v[234:235]
	s_waitcnt vmcnt(0)
	v_mul_f32_e32 v2, v8, v2
	v_mul_f32_e32 v3, v6, v3
	v_cvt_pk_bf16_f32 v2, v2, v3
	v_mul_f32_e32 v3, v23, v9
	v_mul_f32_e32 v3, v3, v4
	v_mul_f32_e32 v4, v23, v7
	v_mul_f32_e32 v4, v4, v5
	v_cvt_pk_bf16_f32 v3, v3, v4
	flat_store_dwordx4 v[24:25], v[0:3] offset:3584
	s_nop 1
	v_add_u32_e32 v0, 0x201, v22
	v_ashrrev_i32_e32 v1, 31, v0
	v_lshlrev_b64 v[0:1], 12, v[0:1]
	v_lshl_add_u64 v[0:1], s[6:7], 0, v[0:1]
	v_lshl_add_u64 v[0:1], v[0:1], 0, v[20:21]
	v_add_co_u32_e32 v28, vcc, s10, v0
	v_lshl_add_u64 v[6:7], v[0:1], 0, s[8:9]
	s_nop 0
	v_addc_co_u32_e32 v29, vcc, 0, v1, vcc
	flat_load_dwordx4 v[2:5], v[28:29] offset:1024
	flat_load_dwordx4 v[8:11], v[6:7] offset:512
	flat_load_dwordx4 v[12:15], v[6:7] offset:1024
	flat_load_dwordx4 v[16:19], v[6:7] offset:1536
	flat_load_dwordx4 v[20:23], v[6:7] offset:2048
	flat_load_dwordx4 v[70:73], v[6:7] offset:2560
	flat_load_dwordx4 v[74:77], v[6:7] offset:3072
	flat_load_dwordx4 v[78:81], v[6:7] offset:3584
	s_waitcnt vmcnt(0) lgkmcnt(0)
	v_and_b32_e32 v0, 0xffff0000, v2
	v_and_b32_e32 v1, 0xffff0000, v3
	v_lshlrev_b32_e32 v82, 16, v2
	v_mul_f32_e32 v24, v0, v0
	v_lshlrev_b32_e32 v2, 16, v3
	v_mul_f32_e32 v3, v1, v1
	v_fmac_f32_e32 v24, v82, v82
	v_fmac_f32_e32 v3, v2, v2
	v_and_b32_e32 v69, 0xffff0000, v4
	v_add_f32_e32 v24, v24, v3
	v_lshlrev_b32_e32 v3, 16, v4
	v_mul_f32_e32 v4, v69, v69
	v_fmac_f32_e32 v4, v3, v3
	v_add_f32_e32 v4, v4, v24
	v_lshlrev_b32_e32 v34, 16, v70
	v_and_b32_e32 v31, 0xffff0000, v70
	v_lshlrev_b32_e32 v33, 16, v71
	v_and_b32_e32 v32, 0xffff0000, v71
	v_lshlrev_b32_e32 v27, 16, v73
	v_lshlrev_b32_e32 v26, 16, v72
	v_and_b32_e32 v25, 0xffff0000, v73
	v_and_b32_e32 v24, 0xffff0000, v72
	s_nop 1
	v_mov_b64_e32 v[70:71], v[172:173]
	v_mov_b64_e32 v[72:73], v[174:175]
	v_and_b32_e32 v67, 0xffff0000, v5
	v_lshlrev_b32_e32 v68, 16, v5
	v_mul_f32_e32 v5, v67, v67
	v_fmac_f32_e32 v5, v68, v68
	v_and_b32_e32 v62, 0xffff0000, v8
	v_add_f32_e32 v4, v5, v4
	v_lshlrev_b32_e32 v66, 16, v8
	v_mul_f32_e32 v5, v62, v62
	v_fmac_f32_e32 v5, v66, v66
	v_and_b32_e32 v63, 0xffff0000, v9
	v_add_f32_e32 v4, v5, v4
	v_lshlrev_b32_e32 v64, 16, v9
	v_mul_f32_e32 v5, v63, v63
	v_fmac_f32_e32 v5, v64, v64
	v_and_b32_e32 v61, 0xffff0000, v10
	v_add_f32_e32 v4, v5, v4
	v_lshlrev_b32_e32 v65, 16, v10
	v_mul_f32_e32 v5, v61, v61
	v_fmac_f32_e32 v5, v65, v65
	v_and_b32_e32 v59, 0xffff0000, v11
	v_add_f32_e32 v4, v5, v4
	v_lshlrev_b32_e32 v60, 16, v11
	v_mul_f32_e32 v5, v59, v59
	v_fmac_f32_e32 v5, v60, v60
	v_and_b32_e32 v54, 0xffff0000, v12
	v_add_f32_e32 v4, v5, v4
	v_lshlrev_b32_e32 v58, 16, v12
	v_mul_f32_e32 v5, v54, v54
	v_fmac_f32_e32 v5, v58, v58
	v_and_b32_e32 v55, 0xffff0000, v13
	v_add_f32_e32 v4, v5, v4
	v_lshlrev_b32_e32 v56, 16, v13
	v_mul_f32_e32 v5, v55, v55
	v_fmac_f32_e32 v5, v56, v56
	v_and_b32_e32 v53, 0xffff0000, v14
	v_add_f32_e32 v4, v5, v4
	v_lshlrev_b32_e32 v57, 16, v14
	v_mul_f32_e32 v5, v53, v53
	v_fmac_f32_e32 v5, v57, v57
	v_and_b32_e32 v51, 0xffff0000, v15
	v_add_f32_e32 v4, v5, v4
	v_lshlrev_b32_e32 v52, 16, v15
; DEVINL unsigned cvtpk(float lo, float hi) { unsigned r; asm("v_cvt_pk_bf16_f32 %0, %1, %2" : "=v"(r) : "v"(lo), "v"(hi)); return r; }
; DEVINL float bflo(unsigned u) { return __uint_as_float(u << 16); }
; DEVINL float bfhi(unsigned u) { return __uint_as_float(u & 0xffff0000u); }
; DEVINL void nak_group(const Params& p, int t, int h) {
;     ...
;   for (int pc = 0; pc < 8; ++pc)
; #pragma unroll
;     for (int j = 0; j < 4; ++j) { const float a = bflo(raw[pc][j]), b = bfhi(raw[pc][j]); ss += a * a + b * b; }
;   const float r = rsqrtf(ss * (1.f / 64.f) + EPS);
; #pragma unroll
;   for (int pc = 0; pc < 8; ++pc) {
;     u32x4 o;
; #pragma unroll
;     for (int j = 0; j < 4; ++j) { const int d = pc * 8 + j * 2; o[j] = cvtpk(bflo(raw[pc][j]) * r * p.nak_w[d], bfhi(raw[pc][j]) * r * p.nak_w[d + 1]); }
;     *reinterpret_cast<u32x4*>(base + pc * 256) = o;
	v_mul_f32_e32 v5, v51, v51
	v_fmac_f32_e32 v5, v52, v52
	v_and_b32_e32 v46, 0xffff0000, v16
	v_add_f32_e32 v4, v5, v4
	v_lshlrev_b32_e32 v50, 16, v16
	v_mul_f32_e32 v5, v46, v46
	v_fmac_f32_e32 v5, v50, v50
	v_and_b32_e32 v47, 0xffff0000, v17
	v_add_f32_e32 v4, v5, v4
	v_lshlrev_b32_e32 v48, 16, v17
	v_mul_f32_e32 v5, v47, v47
	v_fmac_f32_e32 v5, v48, v48
	v_and_b32_e32 v45, 0xffff0000, v18
	v_add_f32_e32 v4, v5, v4
	v_lshlrev_b32_e32 v49, 16, v18
	v_mul_f32_e32 v5, v45, v45
	v_fmac_f32_e32 v5, v49, v49
	v_and_b32_e32 v43, 0xffff0000, v19
	v_add_f32_e32 v4, v5, v4
	v_lshlrev_b32_e32 v44, 16, v19
	v_mul_f32_e32 v5, v43, v43
	v_fmac_f32_e32 v5, v44, v44
	v_and_b32_e32 v38, 0xffff0000, v20
	v_add_f32_e32 v4, v5, v4
	v_lshlrev_b32_e32 v42, 16, v20
	v_mul_f32_e32 v5, v38, v38
	v_fmac_f32_e32 v5, v42, v42
	v_and_b32_e32 v39, 0xffff0000, v21
	v_add_f32_e32 v4, v5, v4
	v_lshlrev_b32_e32 v40, 16, v21
	v_mul_f32_e32 v5, v39, v39
	v_fmac_f32_e32 v5, v40, v40
	v_and_b32_e32 v37, 0xffff0000, v22
	v_add_f32_e32 v4, v5, v4
	v_lshlrev_b32_e32 v41, 16, v22
	v_mul_f32_e32 v5, v37, v37
	v_fmac_f32_e32 v5, v41, v41
	v_and_b32_e32 v35, 0xffff0000, v23
	v_add_f32_e32 v4, v5, v4
	v_lshlrev_b32_e32 v36, 16, v23
	v_mul_f32_e32 v5, v35, v35
	v_fmac_f32_e32 v5, v36, v36
	v_add_f32_e32 v4, v5, v4
	v_mul_f32_e32 v5, v31, v31
	v_fmac_f32_e32 v5, v34, v34
	v_add_f32_e32 v4, v5, v4
	v_mul_f32_e32 v5, v32, v32
	v_fmac_f32_e32 v5, v33, v33
	v_add_f32_e32 v8, v5, v4
	v_pk_mul_f32 v[4:5], v[24:25], v[24:25]
	v_and_b32_e32 v21, 0xffff0000, v75
	v_pk_fma_f32 v[4:5], v[26:27], v[26:27], v[4:5]
	v_and_b32_e32 v20, 0xffff0000, v74
	v_add_f32_e32 v4, v4, v8
	v_add_f32_e32 v8, v5, v4
	v_lshlrev_b32_e32 v23, 16, v75
	v_lshlrev_b32_e32 v22, 16, v74
	v_pk_mul_f32 v[4:5], v[20:21], v[20:21]
	v_and_b32_e32 v17, 0xffff0000, v77
	v_pk_fma_f32 v[4:5], v[22:23], v[22:23], v[4:5]
	v_and_b32_e32 v16, 0xffff0000, v76
	v_add_f32_e32 v4, v4, v8
	v_add_f32_e32 v8, v5, v4
	v_lshlrev_b32_e32 v19, 16, v77
	v_lshlrev_b32_e32 v18, 16, v76
	v_pk_mul_f32 v[4:5], v[16:17], v[16:17]
	v_and_b32_e32 v13, 0xffff0000, v79
	v_pk_fma_f32 v[4:5], v[18:19], v[18:19], v[4:5]
	v_and_b32_e32 v12, 0xffff0000, v78
	v_add_f32_e32 v4, v4, v8
	v_add_f32_e32 v8, v5, v4
	v_lshlrev_b32_e32 v15, 16, v79
	v_lshlrev_b32_e32 v14, 16, v78
	v_pk_mul_f32 v[4:5], v[12:13], v[12:13]
	v_and_b32_e32 v9, 0xffff0000, v81
	v_pk_fma_f32 v[4:5], v[14:15], v[14:15], v[4:5]
	v_lshlrev_b32_e32 v11, 16, v81
	v_add_f32_e32 v4, v4, v8
	v_and_b32_e32 v8, 0xffff0000, v80
	v_add_f32_e32 v30, v5, v4
	v_lshlrev_b32_e32 v10, 16, v80
	v_pk_mul_f32 v[4:5], v[8:9], v[8:9]
	s_nop 0
	v_pk_fma_f32 v[4:5], v[10:11], v[10:11], v[4:5]
	s_nop 0
	v_add_f32_e32 v4, v4, v30
	v_add_f32_e32 v4, v5, v4
	v_fmamk_f32 v4, v4, 0x3c800000, v154
	v_cmp_gt_f32_e32 vcc, s11, v4
	v_mul_f32_e32 v5, 0x4b800000, v4
	s_nop 0
	v_cndmask_b32_e32 v4, v4, v5, vcc
	v_rsq_f32_e32 v4, v4
	s_nop 0
	v_mul_f32_e32 v5, 0x45800000, v4
	v_cndmask_b32_e32 v30, v4, v5, vcc
	v_mul_f32_e32 v4, v30, v82
	v_mul_f32_e32 v0, v30, v0
	v_mul_f32_e32 v2, v30, v2
	v_mul_f32_e32 v1, v30, v1
	s_waitcnt vmcnt(0)
	v_mul_f32_e32 v4, v70, v4
	v_mul_f32_e32 v0, v71, v0
	v_mul_f32_e32 v2, v72, v2
	v_mul_f32_e32 v1, v73, v1
	v_cvt_pk_bf16_f32 v0, v4, v0
	v_cvt_pk_bf16_f32 v1, v2, v1
	v_mul_f32_e32 v70, v30, v3
	s_nop 1
	v_mov_b64_e32 v[2:3], v[176:177]
	v_mov_b64_e32 v[4:5], v[178:179]
	v_mul_f32_e32 v69, v30, v69
	v_mul_f32_e32 v26, v30, v26
	v_mul_f32_e32 v24, v30, v24
	v_mul_f32_e32 v18, v30, v18
	v_mul_f32_e32 v16, v30, v16
	v_mul_f32_e32 v10, v30, v10
	v_mul_f32_e32 v8, v30, v8
	s_waitcnt vmcnt(0)
	v_mul_f32_e32 v2, v2, v70
	v_mul_f32_e32 v3, v3, v69
	v_cvt_pk_bf16_f32 v2, v2, v3
	v_mul_f32_e32 v3, v30, v68
	v_mul_f32_e32 v3, v4, v3
	v_mul_f32_e32 v4, v30, v67
	v_mul_f32_e32 v4, v5, v4
	v_cvt_pk_bf16_f32 v3, v3, v4
	flat_store_dwordx4 v[28:29], v[0:3] offset:1024
	s_nop 1
	v_mov_b64_e32 v[0:1], v[180:181]
	v_mov_b64_e32 v[2:3], v[182:183]
	v_mul_f32_e32 v4, v30, v66
	v_mul_f32_e32 v28, v30, v65
	s_waitcnt vmcnt(0)
	v_mul_f32_e32 v0, v0, v4
	v_mul_f32_e32 v4, v30, v62
	v_mul_f32_e32 v1, v1, v4
	v_cvt_pk_bf16_f32 v0, v0, v1
	v_mul_f32_e32 v1, v30, v64
	v_mul_f32_e32 v1, v2, v1
	v_mul_f32_e32 v2, v30, v63
	v_mul_f32_e32 v2, v3, v2
	v_cvt_pk_bf16_f32 v1, v1, v2
	s_nop 1
	v_mov_b64_e32 v[2:3], v[184:185]
	v_mov_b64_e32 v[4:5], v[186:187]
	s_waitcnt vmcnt(0)
	v_mul_f32_e32 v2, v2, v28
	v_mul_f32_e32 v28, v30, v61
	v_mul_f32_e32 v3, v3, v28
	v_cvt_pk_bf16_f32 v2, v2, v3
	v_mul_f32_e32 v3, v30, v60
	v_mul_f32_e32 v3, v4, v3
	v_mul_f32_e32 v4, v30, v59
	v_mul_f32_e32 v4, v5, v4
	v_cvt_pk_bf16_f32 v3, v3, v4
	flat_store_dwordx4 v[6:7], v[0:3] offset:512
	s_nop 1
	v_mov_b64_e32 v[0:1], v[188:189]
	v_mov_b64_e32 v[2:3], v[190:191]
	v_mul_f32_e32 v4, v30, v58
	v_mul_f32_e32 v28, v30, v57
	s_waitcnt vmcnt(0)
; DEVINL unsigned cvtpk(float lo, float hi) { unsigned r; asm("v_cvt_pk_bf16_f32 %0, %1, %2" : "=v"(r) : "v"(lo), "v"(hi)); return r; }
; DEVINL float bflo(unsigned u) { return __uint_as_float(u << 16); }
; DEVINL float bfhi(unsigned u) { return __uint_as_float(u & 0xffff0000u); }
; DEVINL void nak_group(const Params& p, int t, int h) {
;     ...
;   for (int pc = 0; pc < 8; ++pc) {
;     u32x4 o;
; #pragma unroll
;     for (int j = 0; j < 4; ++j) { const int d = pc * 8 + j * 2; o[j] = cvtpk(bflo(raw[pc][j]) * r * p.nak_w[d], bfhi(raw[pc][j]) * r * p.nak_w[d + 1]); }
;     *reinterpret_cast<u32x4*>(base + pc * 256) = o;
	v_mul_f32_e32 v0, v0, v4
	v_mul_f32_e32 v4, v30, v54
	v_mul_f32_e32 v1, v1, v4
	v_cvt_pk_bf16_f32 v0, v0, v1
	v_mul_f32_e32 v1, v30, v56
	v_mul_f32_e32 v1, v2, v1
	v_mul_f32_e32 v2, v30, v55
	v_mul_f32_e32 v2, v3, v2
	v_cvt_pk_bf16_f32 v1, v1, v2
	s_nop 1
	v_mov_b64_e32 v[2:3], v[192:193]
	v_mov_b64_e32 v[4:5], v[194:195]
	s_waitcnt vmcnt(0)
	v_mul_f32_e32 v2, v2, v28
	v_mul_f32_e32 v28, v30, v53
	v_mul_f32_e32 v3, v3, v28
	v_cvt_pk_bf16_f32 v2, v2, v3
	v_mul_f32_e32 v3, v30, v52
	v_mul_f32_e32 v3, v4, v3
	v_mul_f32_e32 v4, v30, v51
	v_mul_f32_e32 v4, v4, v5
	v_cvt_pk_bf16_f32 v3, v3, v4
	flat_store_dwordx4 v[6:7], v[0:3] offset:1024
	s_nop 1
	v_mov_b64_e32 v[0:1], v[196:197]
	v_mov_b64_e32 v[2:3], v[198:199]
	v_mul_f32_e32 v4, v30, v50
	v_mul_f32_e32 v28, v30, v49
	s_waitcnt vmcnt(0)
	v_mul_f32_e32 v0, v4, v0
	v_mul_f32_e32 v4, v30, v46
	v_mul_f32_e32 v1, v4, v1
	v_cvt_pk_bf16_f32 v0, v0, v1
	v_mul_f32_e32 v1, v30, v48
	v_mul_f32_e32 v1, v1, v2
	v_mul_f32_e32 v2, v30, v47
	v_mul_f32_e32 v2, v2, v3
	v_cvt_pk_bf16_f32 v1, v1, v2
	s_nop 1
	v_mov_b64_e32 v[2:3], v[200:201]
	v_mov_b64_e32 v[4:5], v[202:203]
	s_waitcnt vmcnt(0)
	v_mul_f32_e32 v2, v28, v2
	v_mul_f32_e32 v28, v30, v45
	v_mul_f32_e32 v3, v28, v3
	v_cvt_pk_bf16_f32 v2, v2, v3
	v_mul_f32_e32 v3, v30, v44
	v_mul_f32_e32 v3, v3, v4
	v_mul_f32_e32 v4, v30, v43
	v_mul_f32_e32 v4, v4, v5
	v_cvt_pk_bf16_f32 v3, v3, v4
	flat_store_dwordx4 v[6:7], v[0:3] offset:1536
	s_nop 1
	v_mov_b64_e32 v[0:1], v[204:205]
	v_mov_b64_e32 v[2:3], v[206:207]
	v_mul_f32_e32 v4, v30, v42
	v_mul_f32_e32 v28, v30, v41
	s_waitcnt vmcnt(0)
	v_mul_f32_e32 v0, v4, v0
	v_mul_f32_e32 v4, v30, v38
	v_mul_f32_e32 v1, v4, v1
	v_cvt_pk_bf16_f32 v0, v0, v1
	v_mul_f32_e32 v1, v30, v40
	v_mul_f32_e32 v1, v1, v2
	v_mul_f32_e32 v2, v30, v39
	v_mul_f32_e32 v2, v2, v3
	v_cvt_pk_bf16_f32 v1, v1, v2
	s_nop 1
	v_mov_b64_e32 v[2:3], v[208:209]
	v_mov_b64_e32 v[4:5], v[210:211]
	s_waitcnt vmcnt(0)
	v_mul_f32_e32 v2, v28, v2
	v_mul_f32_e32 v28, v30, v37
	v_mul_f32_e32 v3, v28, v3
	v_cvt_pk_bf16_f32 v2, v2, v3
	v_mul_f32_e32 v3, v30, v36
	v_mul_f32_e32 v3, v3, v4
	v_mul_f32_e32 v4, v30, v35
	v_mul_f32_e32 v4, v4, v5
	v_cvt_pk_bf16_f32 v3, v3, v4
	flat_store_dwordx4 v[6:7], v[0:3] offset:2048
	s_nop 1
	v_mov_b64_e32 v[0:1], v[212:213]
	v_mov_b64_e32 v[2:3], v[214:215]
	v_mul_f32_e32 v4, v30, v34
	s_waitcnt vmcnt(0)
	v_mul_f32_e32 v0, v4, v0
	v_mul_f32_e32 v4, v30, v31
	v_mul_f32_e32 v1, v4, v1
	v_cvt_pk_bf16_f32 v0, v0, v1
	v_mul_f32_e32 v1, v30, v33
	v_mul_f32_e32 v1, v1, v2
	v_mul_f32_e32 v2, v30, v32
	v_mul_f32_e32 v2, v2, v3
	v_cvt_pk_bf16_f32 v1, v1, v2
	s_nop 1
	v_mov_b64_e32 v[2:3], v[216:217]
	v_mov_b64_e32 v[4:5], v[218:219]
	s_waitcnt vmcnt(0)
	v_mul_f32_e32 v2, v26, v2
	v_mul_f32_e32 v3, v24, v3
	v_cvt_pk_bf16_f32 v2, v2, v3
	v_mul_f32_e32 v3, v30, v27
	v_mul_f32_e32 v3, v3, v4
	v_mul_f32_e32 v4, v30, v25
	v_mul_f32_e32 v4, v4, v5
	v_cvt_pk_bf16_f32 v3, v3, v4
	flat_store_dwordx4 v[6:7], v[0:3] offset:2560
	s_nop 1
	v_mov_b64_e32 v[0:1], v[220:221]
	v_mov_b64_e32 v[2:3], v[222:223]
	v_mul_f32_e32 v4, v30, v22
	s_waitcnt vmcnt(0)
	v_mul_f32_e32 v0, v4, v0
	v_mul_f32_e32 v4, v30, v20
	v_mul_f32_e32 v1, v4, v1
	v_cvt_pk_bf16_f32 v0, v0, v1
	v_mul_f32_e32 v1, v30, v23
	v_mul_f32_e32 v1, v1, v2
	v_mul_f32_e32 v2, v30, v21
	v_mul_f32_e32 v2, v2, v3
	v_cvt_pk_bf16_f32 v1, v1, v2
	s_nop 1
	v_mov_b64_e32 v[2:3], v[224:225]
	v_mov_b64_e32 v[4:5], v[226:227]
	s_waitcnt vmcnt(0)
	v_mul_f32_e32 v2, v18, v2
	v_mul_f32_e32 v3, v16, v3
	v_cvt_pk_bf16_f32 v2, v2, v3
	v_mul_f32_e32 v3, v30, v19
	v_mul_f32_e32 v3, v3, v4
	v_mul_f32_e32 v4, v30, v17
	v_mul_f32_e32 v4, v4, v5
	v_cvt_pk_bf16_f32 v3, v3, v4
	flat_store_dwordx4 v[6:7], v[0:3] offset:3072
	s_nop 1
	v_mov_b64_e32 v[0:1], v[228:229]
	v_mov_b64_e32 v[2:3], v[230:231]
	v_mul_f32_e32 v4, v30, v14
	s_waitcnt vmcnt(0)
	v_mul_f32_e32 v0, v4, v0
	v_mul_f32_e32 v4, v30, v12
	v_mul_f32_e32 v1, v4, v1
	v_cvt_pk_bf16_f32 v0, v0, v1
	v_mul_f32_e32 v1, v30, v15
	v_mul_f32_e32 v1, v1, v2
	v_mul_f32_e32 v2, v30, v13
	v_mul_f32_e32 v2, v2, v3
	v_cvt_pk_bf16_f32 v1, v1, v2
	s_nop 1
	v_mov_b64_e32 v[2:3], v[232:233]
	v_mov_b64_e32 v[4:5], v[234:235]
	s_waitcnt vmcnt(0)
	v_mul_f32_e32 v2, v10, v2
	v_mul_f32_e32 v3, v8, v3
	v_cvt_pk_bf16_f32 v2, v2, v3
	v_mul_f32_e32 v3, v30, v11
	v_mul_f32_e32 v3, v3, v4
	v_mul_f32_e32 v4, v30, v9
	v_mul_f32_e32 v4, v4, v5
	v_cvt_pk_bf16_f32 v3, v3, v4
	flat_store_dwordx4 v[6:7], v[0:3] offset:3584
